# P4 LayerNorm row statistics (groups 1-7) rewritten with packed-f32 VALU and permlane swaps instead of mov-packing and ds_bpermute; same two-pass algorithm, f32
# speedup vs baseline: 1.0247x; 1.0047x over previous
.LBB0_502:
	s_or_b64 exec, exec, s[8:9]
	s_waitcnt lgkmcnt(0)
	v_pk_add_f32 v[130:131], v[64:65], v[66:67]
	v_pk_add_f32 v[132:133], v[68:69], v[70:71]
	v_pk_add_f32 v[134:135], v[72:73], v[74:75]
	v_pk_add_f32 v[136:137], v[76:77], v[78:79]
	v_pk_add_f32 v[130:131], v[130:131], v[132:133]
	v_pk_add_f32 v[134:135], v[134:135], v[136:137]
	s_nop 0
	v_pk_add_f32 v[130:131], v[130:131], v[134:135]
	s_nop 0
	v_add_f32_e32 v130, v130, v131
	v_mov_b32_e32 v131, v130
	s_nop 1
	v_permlane16_swap_b32_e32 v130, v131
	v_add_f32_e32 v130, v130, v131
	v_mov_b32_e32 v131, v130
	s_nop 1
	v_permlane32_swap_b32_e32 v130, v131
	v_add_f32_e32 v130, v130, v131
	v_mul_f32_e32 v132, 0xbc800000, v130
	s_nop 0
	v_pk_add_f32 v[134:135], v[64:65], v[132:133] op_sel_hi:[1,0]
	v_pk_add_f32 v[138:139], v[66:67], v[132:133] op_sel_hi:[1,0]
	v_pk_mul_f32 v[136:137], v[134:135], v[134:135]
	v_pk_mul_f32 v[140:141], v[138:139], v[138:139]
	v_pk_add_f32 v[134:135], v[68:69], v[132:133] op_sel_hi:[1,0]
	v_pk_add_f32 v[138:139], v[70:71], v[132:133] op_sel_hi:[1,0]
	v_pk_fma_f32 v[136:137], v[134:135], v[134:135], v[136:137]
	v_pk_fma_f32 v[140:141], v[138:139], v[138:139], v[140:141]
	v_pk_add_f32 v[134:135], v[72:73], v[132:133] op_sel_hi:[1,0]
	v_pk_add_f32 v[138:139], v[74:75], v[132:133] op_sel_hi:[1,0]
	v_pk_fma_f32 v[136:137], v[134:135], v[134:135], v[136:137]
	v_pk_fma_f32 v[140:141], v[138:139], v[138:139], v[140:141]
	v_pk_add_f32 v[134:135], v[76:77], v[132:133] op_sel_hi:[1,0]
	v_pk_add_f32 v[138:139], v[78:79], v[132:133] op_sel_hi:[1,0]
	v_pk_fma_f32 v[136:137], v[134:135], v[134:135], v[136:137]
	v_pk_fma_f32 v[140:141], v[138:139], v[138:139], v[140:141]
	s_nop 0
	v_pk_add_f32 v[136:137], v[136:137], v[140:141]
	s_nop 0
	v_add_f32_e32 v131, v136, v137
	v_mov_b32_e32 v132, v131
	s_nop 1
	v_permlane16_swap_b32_e32 v131, v132
	v_add_f32_e32 v131, v131, v132
	v_mov_b32_e32 v132, v131
	s_nop 1
	v_permlane32_swap_b32_e32 v131, v132
	v_add_f32_e32 v131, v131, v132
	s_and_saveexec_b64 s[8:9], s[2:3]
	s_cbranch_execz .LBB0_504
	v_mul_f32_e32 v130, 0x3c800000, v130
	ds_write_b64 v222, v[130:131] offset:512
.LBB0_504:
	s_or_b64 exec, exec, s[8:9]
	s_waitcnt lgkmcnt(0)
	v_pk_add_f32 v[130:131], v[84:85], v[86:87]
	v_pk_add_f32 v[132:133], v[104:105], v[106:107]
	v_pk_add_f32 v[134:135], v[120:121], v[122:123]
	v_pk_add_f32 v[136:137], v[124:125], v[126:127]
	v_pk_add_f32 v[130:131], v[130:131], v[132:133]
	v_pk_add_f32 v[134:135], v[134:135], v[136:137]
	s_nop 0
	v_pk_add_f32 v[130:131], v[130:131], v[134:135]
	s_nop 0
	v_add_f32_e32 v130, v130, v131
	v_mov_b32_e32 v131, v130
	s_nop 1
	v_permlane16_swap_b32_e32 v130, v131
	v_add_f32_e32 v130, v130, v131
	v_mov_b32_e32 v131, v130
	s_nop 1
	v_permlane32_swap_b32_e32 v130, v131
	v_add_f32_e32 v130, v130, v131
	v_mul_f32_e32 v132, 0xbc800000, v130
	s_nop 0
	v_pk_add_f32 v[134:135], v[84:85], v[132:133] op_sel_hi:[1,0]
	v_pk_add_f32 v[138:139], v[86:87], v[132:133] op_sel_hi:[1,0]
	v_pk_mul_f32 v[136:137], v[134:135], v[134:135]
	v_pk_mul_f32 v[140:141], v[138:139], v[138:139]
	v_pk_add_f32 v[134:135], v[104:105], v[132:133] op_sel_hi:[1,0]
	v_pk_add_f32 v[138:139], v[106:107], v[132:133] op_sel_hi:[1,0]
	v_pk_fma_f32 v[136:137], v[134:135], v[134:135], v[136:137]
	v_pk_fma_f32 v[140:141], v[138:139], v[138:139], v[140:141]
	v_pk_add_f32 v[134:135], v[120:121], v[132:133] op_sel_hi:[1,0]
	v_pk_add_f32 v[138:139], v[122:123], v[132:133] op_sel_hi:[1,0]
	v_pk_fma_f32 v[136:137], v[134:135], v[134:135], v[136:137]
	v_pk_fma_f32 v[140:141], v[138:139], v[138:139], v[140:141]
	v_pk_add_f32 v[134:135], v[124:125], v[132:133] op_sel_hi:[1,0]
	v_pk_add_f32 v[138:139], v[126:127], v[132:133] op_sel_hi:[1,0]
	v_pk_fma_f32 v[136:137], v[134:135], v[134:135], v[136:137]
	v_pk_fma_f32 v[140:141], v[138:139], v[138:139], v[140:141]
	s_nop 0
	v_pk_add_f32 v[136:137], v[136:137], v[140:141]
	s_nop 0
	v_add_f32_e32 v131, v136, v137
	v_mov_b32_e32 v132, v131
	s_nop 1
	v_permlane16_swap_b32_e32 v131, v132
	v_add_f32_e32 v131, v131, v132
	v_mov_b32_e32 v132, v131
	s_nop 1
	v_permlane32_swap_b32_e32 v131, v132
	v_add_f32_e32 v131, v131, v132
	s_and_saveexec_b64 s[8:9], s[2:3]
	s_cbranch_execz .LBB0_506
	v_mul_f32_e32 v130, 0x3c800000, v130
	ds_write_b64 v222, v[130:131] offset:1024
.LBB0_506:
	s_or_b64 exec, exec, s[8:9]
	s_waitcnt lgkmcnt(0)
	v_pk_add_f32 v[130:131], v[80:81], v[82:83]
	v_pk_add_f32 v[132:133], v[88:89], v[90:91]
	v_pk_add_f32 v[134:135], v[112:113], v[114:115]
	v_pk_add_f32 v[136:137], v[116:117], v[118:119]
	v_pk_add_f32 v[130:131], v[130:131], v[132:133]
	v_pk_add_f32 v[134:135], v[134:135], v[136:137]
	s_nop 0
	v_pk_add_f32 v[130:131], v[130:131], v[134:135]
	s_nop 0
	v_add_f32_e32 v130, v130, v131
	v_mov_b32_e32 v131, v130
	s_nop 1
	v_permlane16_swap_b32_e32 v130, v131
	v_add_f32_e32 v130, v130, v131
	v_mov_b32_e32 v131, v130
	s_nop 1
	v_permlane32_swap_b32_e32 v130, v131
	v_add_f32_e32 v130, v130, v131
	v_mul_f32_e32 v132, 0xbc800000, v130
	s_nop 0
	v_pk_add_f32 v[134:135], v[80:81], v[132:133] op_sel_hi:[1,0]
	v_pk_add_f32 v[138:139], v[82:83], v[132:133] op_sel_hi:[1,0]
	v_pk_mul_f32 v[136:137], v[134:135], v[134:135]
	v_pk_mul_f32 v[140:141], v[138:139], v[138:139]
	v_pk_add_f32 v[134:135], v[88:89], v[132:133] op_sel_hi:[1,0]
	v_pk_add_f32 v[138:139], v[90:91], v[132:133] op_sel_hi:[1,0]
	v_pk_fma_f32 v[136:137], v[134:135], v[134:135], v[136:137]
	v_pk_fma_f32 v[140:141], v[138:139], v[138:139], v[140:141]
	v_pk_add_f32 v[134:135], v[112:113], v[132:133] op_sel_hi:[1,0]
	v_pk_add_f32 v[138:139], v[114:115], v[132:133] op_sel_hi:[1,0]
	v_pk_fma_f32 v[136:137], v[134:135], v[134:135], v[136:137]
	v_pk_fma_f32 v[140:141], v[138:139], v[138:139], v[140:141]
	v_pk_add_f32 v[134:135], v[116:117], v[132:133] op_sel_hi:[1,0]
	v_pk_add_f32 v[138:139], v[118:119], v[132:133] op_sel_hi:[1,0]
	v_pk_fma_f32 v[136:137], v[134:135], v[134:135], v[136:137]
	v_pk_fma_f32 v[140:141], v[138:139], v[138:139], v[140:141]
	s_nop 0
	v_pk_add_f32 v[136:137], v[136:137], v[140:141]
	s_nop 0
	v_add_f32_e32 v131, v136, v137
	v_mov_b32_e32 v132, v131
	s_nop 1
	v_permlane16_swap_b32_e32 v131, v132
	v_add_f32_e32 v131, v131, v132
	v_mov_b32_e32 v132, v131
	s_nop 1
	v_permlane32_swap_b32_e32 v131, v132
	v_add_f32_e32 v131, v131, v132
	s_and_saveexec_b64 s[8:9], s[2:3]
	s_cbranch_execz .LBB0_508
	v_mul_f32_e32 v130, 0x3c800000, v130
	ds_write_b64 v222, v[130:131] offset:1536
.LBB0_508:
	s_or_b64 exec, exec, s[8:9]
	s_waitcnt lgkmcnt(0)
	v_pk_add_f32 v[130:131], v[0:1], v[2:3]
	v_pk_add_f32 v[132:133], v[4:5], v[6:7]
	v_pk_add_f32 v[134:135], v[12:13], v[14:15]
	v_pk_add_f32 v[136:137], v[20:21], v[22:23]
	v_pk_add_f32 v[130:131], v[130:131], v[132:133]
	v_pk_add_f32 v[134:135], v[134:135], v[136:137]
	s_nop 0
	v_pk_add_f32 v[130:131], v[130:131], v[134:135]
	s_nop 0
	v_add_f32_e32 v130, v130, v131
	v_mov_b32_e32 v131, v130
	s_nop 1
	v_permlane16_swap_b32_e32 v130, v131
	v_add_f32_e32 v130, v130, v131
	v_mov_b32_e32 v131, v130
	s_nop 1
	v_permlane32_swap_b32_e32 v130, v131
	v_add_f32_e32 v130, v130, v131
	v_mul_f32_e32 v132, 0xbc800000, v130
	s_nop 0
	v_pk_add_f32 v[134:135], v[0:1], v[132:133] op_sel_hi:[1,0]
	v_pk_add_f32 v[138:139], v[2:3], v[132:133] op_sel_hi:[1,0]
	v_pk_mul_f32 v[136:137], v[134:135], v[134:135]
	v_pk_mul_f32 v[140:141], v[138:139], v[138:139]
	v_pk_add_f32 v[134:135], v[4:5], v[132:133] op_sel_hi:[1,0]
	v_pk_add_f32 v[138:139], v[6:7], v[132:133] op_sel_hi:[1,0]
	v_pk_fma_f32 v[136:137], v[134:135], v[134:135], v[136:137]
	v_pk_fma_f32 v[140:141], v[138:139], v[138:139], v[140:141]
	v_pk_add_f32 v[134:135], v[12:13], v[132:133] op_sel_hi:[1,0]
	v_pk_add_f32 v[138:139], v[14:15], v[132:133] op_sel_hi:[1,0]
	v_pk_fma_f32 v[136:137], v[134:135], v[134:135], v[136:137]
	v_pk_fma_f32 v[140:141], v[138:139], v[138:139], v[140:141]
	v_pk_add_f32 v[134:135], v[20:21], v[132:133] op_sel_hi:[1,0]
	v_pk_add_f32 v[138:139], v[22:23], v[132:133] op_sel_hi:[1,0]
	v_pk_fma_f32 v[136:137], v[134:135], v[134:135], v[136:137]
	v_pk_fma_f32 v[140:141], v[138:139], v[138:139], v[140:141]
	s_nop 0
	v_pk_add_f32 v[136:137], v[136:137], v[140:141]
	s_nop 0
	v_add_f32_e32 v131, v136, v137
	v_mov_b32_e32 v132, v131
	s_nop 1
	v_permlane16_swap_b32_e32 v131, v132
	v_add_f32_e32 v131, v131, v132
	v_mov_b32_e32 v132, v131
	s_nop 1
	v_permlane32_swap_b32_e32 v131, v132
	v_add_f32_e32 v131, v131, v132
	s_and_saveexec_b64 s[8:9], s[2:3]
	s_cbranch_execz .LBB0_510
	v_mul_f32_e32 v130, 0x3c800000, v130
	ds_write_b64 v222, v[130:131] offset:4096
.LBB0_510:
	s_or_b64 exec, exec, s[8:9]
	s_waitcnt lgkmcnt(0)
	v_pk_add_f32 v[130:131], v[8:9], v[10:11]
	v_pk_add_f32 v[132:133], v[16:17], v[18:19]
	v_pk_add_f32 v[134:135], v[24:25], v[26:27]
	v_pk_add_f32 v[136:137], v[28:29], v[30:31]
	v_pk_add_f32 v[130:131], v[130:131], v[132:133]
	v_pk_add_f32 v[134:135], v[134:135], v[136:137]
	s_nop 0
	v_pk_add_f32 v[130:131], v[130:131], v[134:135]
	s_nop 0
	v_add_f32_e32 v130, v130, v131
	v_mov_b32_e32 v131, v130
	s_nop 1
	v_permlane16_swap_b32_e32 v130, v131
	v_add_f32_e32 v130, v130, v131
	v_mov_b32_e32 v131, v130
	s_nop 1
	v_permlane32_swap_b32_e32 v130, v131
	v_add_f32_e32 v130, v130, v131
	v_mul_f32_e32 v132, 0xbc800000, v130
	s_nop 0
	v_pk_add_f32 v[134:135], v[8:9], v[132:133] op_sel_hi:[1,0]
	v_pk_add_f32 v[138:139], v[10:11], v[132:133] op_sel_hi:[1,0]
	v_pk_mul_f32 v[136:137], v[134:135], v[134:135]
	v_pk_mul_f32 v[140:141], v[138:139], v[138:139]
	v_pk_add_f32 v[134:135], v[16:17], v[132:133] op_sel_hi:[1,0]
	v_pk_add_f32 v[138:139], v[18:19], v[132:133] op_sel_hi:[1,0]
	v_pk_fma_f32 v[136:137], v[134:135], v[134:135], v[136:137]
	v_pk_fma_f32 v[140:141], v[138:139], v[138:139], v[140:141]
	v_pk_add_f32 v[134:135], v[24:25], v[132:133] op_sel_hi:[1,0]
	v_pk_add_f32 v[138:139], v[26:27], v[132:133] op_sel_hi:[1,0]
	v_pk_fma_f32 v[136:137], v[134:135], v[134:135], v[136:137]
	v_pk_fma_f32 v[140:141], v[138:139], v[138:139], v[140:141]
	v_pk_add_f32 v[134:135], v[28:29], v[132:133] op_sel_hi:[1,0]
	v_pk_add_f32 v[138:139], v[30:31], v[132:133] op_sel_hi:[1,0]
	v_pk_fma_f32 v[136:137], v[134:135], v[134:135], v[136:137]
	v_pk_fma_f32 v[140:141], v[138:139], v[138:139], v[140:141]
	s_nop 0
	v_pk_add_f32 v[136:137], v[136:137], v[140:141]
	s_nop 0
	v_add_f32_e32 v131, v136, v137
	v_mov_b32_e32 v132, v131
	s_nop 1
	v_permlane16_swap_b32_e32 v131, v132
	v_add_f32_e32 v131, v131, v132
	v_mov_b32_e32 v132, v131
	s_nop 1
	v_permlane32_swap_b32_e32 v131, v132
	v_add_f32_e32 v131, v131, v132
	s_and_saveexec_b64 s[8:9], s[2:3]
	s_cbranch_execz .LBB0_512
	v_mul_f32_e32 v130, 0x3c800000, v130
	ds_write_b64 v222, v[130:131] offset:4608
.LBB0_512:
	s_or_b64 exec, exec, s[8:9]
	s_waitcnt lgkmcnt(0)
	v_pk_add_f32 v[130:131], v[32:33], v[34:35]
	v_pk_add_f32 v[132:133], v[36:37], v[38:39]
	v_pk_add_f32 v[134:135], v[40:41], v[42:43]
	v_pk_add_f32 v[136:137], v[44:45], v[46:47]
	v_pk_add_f32 v[130:131], v[130:131], v[132:133]
	v_pk_add_f32 v[134:135], v[134:135], v[136:137]
	s_nop 0
	v_pk_add_f32 v[130:131], v[130:131], v[134:135]
	s_nop 0
	v_add_f32_e32 v130, v130, v131
	v_mov_b32_e32 v131, v130
	s_nop 1
	v_permlane16_swap_b32_e32 v130, v131
	v_add_f32_e32 v130, v130, v131
	v_mov_b32_e32 v131, v130
	s_nop 1
	v_permlane32_swap_b32_e32 v130, v131
	v_add_f32_e32 v130, v130, v131
	v_mul_f32_e32 v132, 0xbc800000, v130
	s_nop 0
	v_pk_add_f32 v[134:135], v[32:33], v[132:133] op_sel_hi:[1,0]
	v_pk_add_f32 v[138:139], v[34:35], v[132:133] op_sel_hi:[1,0]
	v_pk_mul_f32 v[136:137], v[134:135], v[134:135]
	v_pk_mul_f32 v[140:141], v[138:139], v[138:139]
	v_pk_add_f32 v[134:135], v[36:37], v[132:133] op_sel_hi:[1,0]
	v_pk_add_f32 v[138:139], v[38:39], v[132:133] op_sel_hi:[1,0]
	v_pk_fma_f32 v[136:137], v[134:135], v[134:135], v[136:137]
	v_pk_fma_f32 v[140:141], v[138:139], v[138:139], v[140:141]
	v_pk_add_f32 v[134:135], v[40:41], v[132:133] op_sel_hi:[1,0]
	v_pk_add_f32 v[138:139], v[42:43], v[132:133] op_sel_hi:[1,0]
	v_pk_fma_f32 v[136:137], v[134:135], v[134:135], v[136:137]
	v_pk_fma_f32 v[140:141], v[138:139], v[138:139], v[140:141]
	v_pk_add_f32 v[134:135], v[44:45], v[132:133] op_sel_hi:[1,0]
	v_pk_add_f32 v[138:139], v[46:47], v[132:133] op_sel_hi:[1,0]
	v_pk_fma_f32 v[136:137], v[134:135], v[134:135], v[136:137]
	v_pk_fma_f32 v[140:141], v[138:139], v[138:139], v[140:141]
	s_nop 0
	v_pk_add_f32 v[136:137], v[136:137], v[140:141]
	s_nop 0
	v_add_f32_e32 v131, v136, v137
	v_mov_b32_e32 v132, v131
	s_nop 1
	v_permlane16_swap_b32_e32 v131, v132
	v_add_f32_e32 v131, v131, v132
	v_mov_b32_e32 v132, v131
	s_nop 1
	v_permlane32_swap_b32_e32 v131, v132
	v_add_f32_e32 v131, v131, v132
	s_and_saveexec_b64 s[8:9], s[2:3]
	s_cbranch_execz .LBB0_514
	v_mul_f32_e32 v130, 0x3c800000, v130
	ds_write_b64 v222, v[130:131] offset:5120
.LBB0_514:
	s_or_b64 exec, exec, s[8:9]
	s_waitcnt lgkmcnt(0)
	v_pk_add_f32 v[130:131], v[48:49], v[50:51]
	v_pk_add_f32 v[132:133], v[52:53], v[54:55]
	v_pk_add_f32 v[134:135], v[56:57], v[58:59]
	v_pk_add_f32 v[136:137], v[60:61], v[62:63]
	v_pk_add_f32 v[130:131], v[130:131], v[132:133]
	v_pk_add_f32 v[134:135], v[134:135], v[136:137]
	s_nop 0
	v_pk_add_f32 v[130:131], v[130:131], v[134:135]
	s_nop 0
	v_add_f32_e32 v130, v130, v131
	v_mov_b32_e32 v131, v130
	s_nop 1
	v_permlane16_swap_b32_e32 v130, v131
	v_add_f32_e32 v130, v130, v131
	v_mov_b32_e32 v131, v130
	s_nop 1
	v_permlane32_swap_b32_e32 v130, v131
	v_add_f32_e32 v130, v130, v131
	v_mul_f32_e32 v132, 0xbc800000, v130
	s_nop 0
	v_pk_add_f32 v[134:135], v[48:49], v[132:133] op_sel_hi:[1,0]
	v_pk_add_f32 v[138:139], v[50:51], v[132:133] op_sel_hi:[1,0]
	v_pk_mul_f32 v[136:137], v[134:135], v[134:135]
	v_pk_mul_f32 v[140:141], v[138:139], v[138:139]
	v_pk_add_f32 v[134:135], v[52:53], v[132:133] op_sel_hi:[1,0]
	v_pk_add_f32 v[138:139], v[54:55], v[132:133] op_sel_hi:[1,0]
	v_pk_fma_f32 v[136:137], v[134:135], v[134:135], v[136:137]
	v_pk_fma_f32 v[140:141], v[138:139], v[138:139], v[140:141]
	v_pk_add_f32 v[134:135], v[56:57], v[132:133] op_sel_hi:[1,0]
	v_pk_add_f32 v[138:139], v[58:59], v[132:133] op_sel_hi:[1,0]
	v_pk_fma_f32 v[136:137], v[134:135], v[134:135], v[136:137]
	v_pk_fma_f32 v[140:141], v[138:139], v[138:139], v[140:141]
	v_pk_add_f32 v[134:135], v[60:61], v[132:133] op_sel_hi:[1,0]
	v_pk_add_f32 v[138:139], v[62:63], v[132:133] op_sel_hi:[1,0]
	v_pk_fma_f32 v[136:137], v[134:135], v[134:135], v[136:137]
	v_pk_fma_f32 v[140:141], v[138:139], v[138:139], v[140:141]
	s_nop 0
	v_pk_add_f32 v[136:137], v[136:137], v[140:141]
	s_nop 0
	v_add_f32_e32 v131, v136, v137
	v_mov_b32_e32 v132, v131
	s_nop 1
	v_permlane16_swap_b32_e32 v131, v132
	v_add_f32_e32 v131, v131, v132
	v_mov_b32_e32 v132, v131
	s_nop 1
	v_permlane32_swap_b32_e32 v131, v132
	v_add_f32_e32 v131, v131, v132
	s_and_saveexec_b64 s[8:9], s[2:3]
	s_cbranch_execz .LBB0_516
	v_mul_f32_e32 v130, 0x3c800000, v130
	ds_write_b64 v222, v[130:131] offset:5632
